# counted waits: store-drain waits at the KV and Q up-projection phase ends removed (loads incl. LDS-DMA are already drained by the epilogue's own wait); fused Q prologue's empty waits removed
# baseline (speedup 1.0000x reference)
; #define PG8_WAIT_V(n) asm volatile("s_waitcnt vmcnt(" #n ")" ::: "memory")
; #define PG8_BAR __builtin_amdgcn_s_barrier()
; template <class Epi, class Sched>
; __device__ __forceinline__ void gemm_phase(LAS unsigned char* lds, const Gemm g, const Sched& S, const Epi& E) {
;     ...
;     PG8_WAIT_V(0);
;     PG8_BAR;
.LBB0_425:
	s_nop 0
	s_barrier

; #define PG8_STAGE(bufoff, gbase, voff) do { _Pragma("unroll") for (int _i = 0; _i < 2; ++_i) \
;         __builtin_amdgcn_global_load_lds((const unsigned*)((const char*)(gbase) + (voff)[_i]), (LAS unsigned*)(lds + (bufoff) + ldsw + _i * 8192), 16, 0, 0); } while (0)
; #define PG8_WAIT_V(n) asm volatile("s_waitcnt vmcnt(" #n ")" ::: "memory")
; #define PG8_BAR __builtin_amdgcn_s_barrier()
; template <class Epi, class Sched>
; __device__ __forceinline__ void gemm_phase(LAS unsigned char* lds, const Gemm g, const Sched& S, const Epi& E) {
;     ...
;     const char* cA = (const char*)g.A + (size_t)cur.pm * tsA; const char* cB = (const char*)g.Bt + (size_t)cur.pn * tsB;
;     PG8_STAGE(PG8_SB(0, 0), cB, voffB); PG8_STAGE(PG8_SB(0, 1), cB + hsB, voffB); PG8_STAGE(PG8_SA(0, 0), cA, voffA); PG8_STAGE(PG8_SA(0, 1), cA + hsA, voffA);
;     if (wr == 1) PG8_BAR;
;     PG8_WAIT_V(2); PG8_BAR;
;     PG8_STAGE(PG8_SB(1, 0), cB + kstep, voffB); PG8_STAGE(PG8_SA(1, 0), cA + kstep, voffA); PG8_STAGE(PG8_SB(1, 1), cB + hsB + kstep, voffB);
;     PG8_WAIT_V(6); PG8_BAR;
.Lkvq_431:
	s_add_u32 s12, s82, 0xbd80000
	s_mov_b64 s[22:23], 0x80
	s_addc_u32 s13, s83, 0
	s_lshl_b32 s0, s0, 5
	s_add_i32 m0, s46, 0x18000
	v_lshl_add_u64 v[6:7], v[6:7], 0, s[22:23]
	s_lshl_b32 s51, s1, 6
	s_lshl_b32 s5, s1, 13
	s_and_b32 s7, s0, 0x60
	s_nop 0
	s_barrier
	v_lshl_add_u64 v[4:5], v[4:5], 0, s[22:23]
	s_add_i32 m0, s46, 0x1a000
	s_add_i32 s53, s46, 0x8000
	s_add_i32 s54, s46, 0xa000
	v_lshl_add_u64 v[0:1], v[0:1], 0, s[22:23]
	s_mov_b32 m0, s53
	s_add_u32 s0, s8, 0x20080
	v_lshl_add_u64 v[0:1], v[2:3], 0, s[22:23]
	s_mov_b32 m0, s54
	s_addc_u32 s1, s9, 0
	s_add_i32 m0, s46, 0x1c000
	v_lshl_add_u64 v[0:1], s[0:1], 0, v[130:131]
	v_lshl_add_u64 v[0:1], s[0:1], 0, v[134:135]
	s_add_i32 m0, s46, 0x1e000
	s_cmpk_lt_u32 s4, 0x100
	v_lshlrev_b32_e32 v1, 2, v179
	v_lshl_or_b32 v0, v179, 6, v163
	v_and_b32_e32 v1, 32, v1
	v_bitop3_b32 v0, v0, s5, v1 bitop3:0xde
	s_nop 0
	v_lshl_or_b32 v149, s7, 7, v164
	s_cselect_b64 s[26:27], -1, 0
	s_add_i32 s67, 0, 0x10000
	s_add_i32 s68, 0, 0x14000
	v_add_u32_e32 v182, 0, v0
	v_mbcnt_lo_u32_b32 v0, -1, 0
	v_lshl_add_u64 v[138:139], s[60:61], 0, v[136:137]
	s_ashr_i32 s55, s58, 31
	s_mov_b32 s64, s58
	s_ashr_i32 s65, s40, 31
	v_or_b32_e32 v151, s7, v136
	v_add3_u32 v140, v161, v155, v157
	v_mov_b32_e32 v141, v137
	v_add3_u32 v142, v162, v155, v157
	v_mov_b32_e32 v143, v137
	v_mov_b64_e32 v[144:145], 0xc0
	v_mov_b64_e32 v[146:147], 0xbf
	s_mov_b32 s66, 0x2aaaaaab
	v_add_u32_e32 v180, s67, v149
	v_add_u32_e32 v181, s68, v149
	s_movk_i32 s69, 0x80
	v_mbcnt_hi_u32_b32 v183, -1, v0
	s_mov_b32 s28, 0x3b000000
	s_mov_b32 s70, 0x800000
	s_movk_i32 s71, 0xff40
	s_movk_i32 s72, 0x7f
	s_movk_i32 s73, 0x180
	v_mov_b32_e32 v148, 0x358637bd
	v_mov_b32_e32 v184, 0xfcf
	s_barrier
	s_branch .LBB0_434
